# best_v12 + layer-0 prep LoRA ladder de-serialised (16 operand loads together, counted waits)
# baseline (speedup 1.0000x reference)
.LBB0_227:
	s_or_b64 exec, exec, s[4:5]
	s_waitcnt vmcnt(0)
	v_cvt_f32_f16_sdwa v19, v0 dst_sel:DWORD dst_unused:UNUSED_PAD src0_sel:WORD_1
	v_cvt_f32_f16_e32 v18, v0
	v_add_u32_e32 v82, s3, v95
	v_ashrrev_i32_e32 v83, 31, v82
	v_lshlrev_b64 v[76:77], 10, v[82:83]
	v_pk_add_f32 v[20:21], v[10:11], v[18:19] neg_lo:[0,1] neg_hi:[0,1]
	global_load_dwordx4 v[8:11], v[28:29], off offset:16
	global_load_dwordx4 v[14:17], v[28:29], off
	v_lshl_add_u64 v[86:87], v[42:43], 0, v[76:77]
	s_add_i32 s10, s10, s28
	s_waitcnt vmcnt(0)
	v_pk_fma_f32 v[14:15], v[14:15], v[20:21], v[18:19]
	s_nop 0
	v_add_f32_e32 v0, v14, v14
	v_mul_f32_e32 v0, 0x3fb8aa3b, v0
	v_exp_f32_e32 v0, v0
	s_nop 0
	v_add_f32_e32 v0, 1.0, v0
	v_rcp_f32_e32 v18, v0
	v_add_f32_e32 v0, v15, v15
	v_mul_f32_e32 v0, 0x3fb8aa3b, v0
	v_exp_f32_e32 v0, v0
	s_nop 0
	v_add_f32_e32 v0, 1.0, v0
	v_rcp_f32_e32 v19, v0
	s_nop 0
	v_pk_fma_f32 v[18:19], v[18:19], 2.0, 1.0 op_sel_hi:[1,0,0] neg_lo:[1,0,0] neg_hi:[1,0,0]
	s_nop 0
	v_cndmask_b32_e64 v0, v15, v19, s[0:1]
	v_cndmask_b32_e64 v14, v14, v18, s[0:1]
	v_cvt_pk_f16_f32 v0, v14, v0
	v_cvt_f32_f16_sdwa v15, v1 dst_sel:DWORD dst_unused:UNUSED_PAD src0_sel:WORD_1
	v_cvt_f32_f16_e32 v14, v1
	v_pk_add_f32 v[12:13], v[12:13], v[14:15] neg_lo:[0,1] neg_hi:[0,1]
	s_nop 0
	v_pk_fma_f32 v[12:13], v[12:13], v[16:17], v[14:15]
	s_nop 0
	v_add_f32_e32 v1, v12, v12
	v_mul_f32_e32 v1, 0x3fb8aa3b, v1
	v_exp_f32_e32 v1, v1
	s_nop 0
	v_add_f32_e32 v1, 1.0, v1
	v_rcp_f32_e32 v14, v1
	v_add_f32_e32 v1, v13, v13
	v_mul_f32_e32 v1, 0x3fb8aa3b, v1
	v_exp_f32_e32 v1, v1
	s_nop 0
	v_add_f32_e32 v1, 1.0, v1
	v_rcp_f32_e32 v15, v1
	s_nop 0
	v_pk_fma_f32 v[14:15], v[14:15], 2.0, 1.0 op_sel_hi:[1,0,0] neg_lo:[1,0,0] neg_hi:[1,0,0]
	s_nop 0
	v_cndmask_b32_e64 v1, v13, v15, s[0:1]
	v_cndmask_b32_e64 v12, v12, v14, s[0:1]
	v_cvt_pk_f16_f32 v1, v12, v1
	v_cvt_f32_f16_sdwa v13, v2 dst_sel:DWORD dst_unused:UNUSED_PAD src0_sel:WORD_1
	v_cvt_f32_f16_e32 v12, v2
	v_pk_add_f32 v[4:5], v[4:5], v[12:13] neg_lo:[0,1] neg_hi:[0,1]
	s_nop 0
	v_pk_fma_f32 v[4:5], v[4:5], v[8:9], v[12:13]
	s_nop 0
	v_add_f32_e32 v2, v4, v4
	v_mul_f32_e32 v2, 0x3fb8aa3b, v2
	v_exp_f32_e32 v2, v2
	s_nop 0
	v_add_f32_e32 v2, 1.0, v2
	v_rcp_f32_e32 v8, v2
	v_add_f32_e32 v2, v5, v5
	v_mul_f32_e32 v2, 0x3fb8aa3b, v2
	v_exp_f32_e32 v2, v2
	s_nop 0
	v_add_f32_e32 v2, 1.0, v2
	v_rcp_f32_e32 v9, v2
	s_nop 0
	v_pk_fma_f32 v[8:9], v[8:9], 2.0, 1.0 op_sel_hi:[1,0,0] neg_lo:[1,0,0] neg_hi:[1,0,0]
	s_nop 0
	v_cndmask_b32_e64 v2, v5, v9, s[0:1]
	v_cndmask_b32_e64 v4, v4, v8, s[0:1]
	v_cvt_pk_f16_f32 v2, v4, v2
	v_cvt_f32_f16_sdwa v5, v3 dst_sel:DWORD dst_unused:UNUSED_PAD src0_sel:WORD_1
	v_cvt_f32_f16_e32 v4, v3
	v_pk_add_f32 v[6:7], v[6:7], v[4:5] neg_lo:[0,1] neg_hi:[0,1]
	s_nop 0
	v_pk_fma_f32 v[4:5], v[6:7], v[10:11], v[4:5]
	s_nop 0
	v_add_f32_e32 v3, v4, v4
	v_mul_f32_e32 v3, 0x3fb8aa3b, v3
	v_exp_f32_e32 v3, v3
	s_nop 0
	v_add_f32_e32 v3, 1.0, v3
	v_rcp_f32_e32 v6, v3
	v_add_f32_e32 v3, v5, v5
	v_mul_f32_e32 v3, 0x3fb8aa3b, v3
	v_exp_f32_e32 v3, v3
	s_nop 0
	v_add_f32_e32 v3, 1.0, v3
	v_rcp_f32_e32 v7, v3
	s_nop 0
	v_pk_fma_f32 v[6:7], v[6:7], 2.0, 1.0 op_sel_hi:[1,0,0] neg_lo:[1,0,0] neg_hi:[1,0,0]
	s_nop 0
	v_cndmask_b32_e64 v3, v5, v7, s[0:1]
	v_cndmask_b32_e64 v4, v4, v6, s[0:1]
	v_cvt_pk_f16_f32 v3, v4, v3
	ds_write_b128 v93, v[0:3]
	s_waitcnt lgkmcnt(0)
	s_barrier
	ds_read_b128 v[12:15], v94
	ds_read_b128 v[8:11], v94 offset:2304
	ds_read_b128 v[4:7], v94 offset:64
	ds_read_b128 v[0:3], v94 offset:2368
	global_load_dwordx4 v[20:23], v[34:35], off
	global_load_dwordx4 v[16:19], v[32:33], off
	s_waitcnt vmcnt(1) lgkmcnt(2)
	v_mfma_f32_16x16x32_f16 v[78:81], v[8:11], v[20:23], 0
	global_load_dwordx4 v[20:23], v[32:33], off offset:64
	s_waitcnt vmcnt(1)
	v_mfma_f32_16x16x32_f16 v[16:19], v[12:15], v[16:19], 0
	s_waitcnt vmcnt(0) lgkmcnt(1)
	v_mfma_f32_16x16x32_f16 v[20:23], v[4:7], v[20:23], v[16:19]
	s_nop 5
	global_load_dwordx4 v[16:19], v[36:37], off
	global_load_dword v99, v[38:39], off
	global_load_dword v100, v[40:41], off
	s_waitcnt vmcnt(1)
	v_add_f32_e32 v20, v20, v99
	s_waitcnt lgkmcnt(0)
	v_mfma_f32_16x16x32_f16 v[16:19], v[0:3], v[16:19], v[78:81]
	v_mul_f32_e32 v20, 0xbfb8aa3b, v20
	v_exp_f32_e32 v20, v20
	s_nop 0
	v_add_u32_e32 v78, 1, v82
	v_ashrrev_i32_e32 v79, 31, v78
	s_waitcnt vmcnt(0)
	s_nop 1
	v_add_f32_e32 v16, v16, v100
	v_mul_f32_e32 v16, 0xbfb8aa3b, v16
	v_exp_f32_e32 v16, v16
	v_lshlrev_b64 v[78:79], 10, v[78:79]
	v_lshl_add_u64 v[88:89], v[42:43], 0, v[78:79]
	v_add_f32_e32 v20, 1.0, v20
	v_add_f32_e32 v16, 1.0, v16
	v_rcp_f32_e32 v16, v16
	v_rcp_f32_e32 v20, v20
	v_cvt_f16_f32_e32 v16, v16
	v_mul_f32_e32 v20, 0xbf1b4598, v20
	v_mul_f32_e32 v20, 0x3fb8aa3b, v20
	v_exp_f32_e32 v20, v20
	global_store_short v[86:87], v16, off offset:512
	v_add_f32_e32 v16, v21, v99
	v_mul_f32_e32 v16, 0xbfb8aa3b, v16
	v_exp_f32_e32 v16, v16
	v_cvt_f16_f32_e32 v20, v20
	v_add_f32_e32 v16, 1.0, v16
	v_rcp_f32_e32 v16, v16
	global_store_short v[86:87], v20, off
	v_mul_f32_e32 v16, 0xbf1b4598, v16
	v_mul_f32_e32 v16, 0x3fb8aa3b, v16
	v_exp_f32_e32 v16, v16
	s_nop 0
	v_cvt_f16_f32_e32 v16, v16
	global_store_short v[88:89], v16, off
	v_add_f32_e32 v16, v17, v100
	v_mul_f32_e32 v16, 0xbfb8aa3b, v16
	v_exp_f32_e32 v16, v16
	s_nop 0
	v_add_f32_e32 v16, 1.0, v16
	v_rcp_f32_e32 v16, v16
	s_nop 0
	v_cvt_f16_f32_e32 v16, v16
	global_store_short v[88:89], v16, off offset:512
	v_add_u32_e32 v16, 2, v82
	v_ashrrev_i32_e32 v17, 31, v16
	v_lshlrev_b64 v[80:81], 10, v[16:17]
	v_add_f32_e32 v16, v22, v99
	v_mul_f32_e32 v16, 0xbfb8aa3b, v16
	v_exp_f32_e32 v16, v16
	v_lshl_add_u64 v[90:91], v[42:43], 0, v[80:81]
	v_add_f32_e32 v16, 1.0, v16
	v_rcp_f32_e32 v16, v16
	s_nop 0
	v_mul_f32_e32 v16, 0xbf1b4598, v16
	v_mul_f32_e32 v16, 0x3fb8aa3b, v16
	v_exp_f32_e32 v16, v16
	s_nop 0
	v_cvt_f16_f32_e32 v16, v16
	global_store_short v[90:91], v16, off
	v_add_f32_e32 v16, v18, v100
	v_mul_f32_e32 v16, 0xbfb8aa3b, v16
	v_exp_f32_e32 v16, v16
	s_nop 0
	v_add_f32_e32 v16, 1.0, v16
	v_rcp_f32_e32 v16, v16
	s_nop 0
	v_cvt_f16_f32_e32 v16, v16
	global_store_short v[90:91], v16, off offset:512
	v_add_u32_e32 v16, 3, v82
	v_ashrrev_i32_e32 v17, 31, v16
	v_lshlrev_b64 v[82:83], 10, v[16:17]
	v_add_f32_e32 v16, v23, v99
	v_mul_f32_e32 v16, 0xbfb8aa3b, v16
	v_exp_f32_e32 v16, v16
	v_lshl_add_u64 v[84:85], v[42:43], 0, v[82:83]
	v_add_f32_e32 v16, 1.0, v16
	v_rcp_f32_e32 v16, v16
	s_nop 0
	v_mul_f32_e32 v16, 0xbf1b4598, v16
	v_mul_f32_e32 v16, 0x3fb8aa3b, v16
	v_exp_f32_e32 v16, v16
	s_nop 0
	v_cvt_f16_f32_e32 v16, v16
	global_store_short v[84:85], v16, off
	v_add_f32_e32 v16, v19, v100
	v_mul_f32_e32 v16, 0xbfb8aa3b, v16
	v_exp_f32_e32 v16, v16
	s_nop 0
	v_add_f32_e32 v16, 1.0, v16
	v_rcp_f32_e32 v16, v16
	s_nop 0
	v_cvt_f16_f32_e32 v16, v16
	global_store_short v[84:85], v16, off offset:512
	global_load_dwordx4 v[16:19], v[44:45], off
	s_nop 0
	global_load_dwordx4 v[100:103], v[44:45], off offset:64
	global_load_dwordx4 v[20:23], v[46:47], off
	s_waitcnt vmcnt(2)
	v_mfma_f32_16x16x32_f16 v[16:19], v[12:15], v[16:19], 0
	s_waitcnt vmcnt(1)
	v_mfma_f32_16x16x32_f16 v[16:19], v[4:7], v[100:103], v[16:19]
	global_load_dwordx4 v[100:103], v[48:49], off
	s_waitcnt vmcnt(1)
	v_mfma_f32_16x16x32_f16 v[20:23], v[8:11], v[20:23], 0
	s_waitcnt vmcnt(0)
	v_mfma_f32_16x16x32_f16 v[20:23], v[0:3], v[100:103], v[20:23]
	global_load_dword v99, v[38:39], off offset:64
	global_load_dword v100, v[40:41], off offset:64
	s_waitcnt vmcnt(1)
	v_add_f32_e32 v16, v16, v99
	v_mul_f32_e32 v16, 0xbfb8aa3b, v16
	v_exp_f32_e32 v16, v16
	s_nop 0
	v_add_f32_e32 v16, 1.0, v16
	v_rcp_f32_e32 v16, v16
	s_nop 0
	v_mul_f32_e32 v16, 0xbf1b4598, v16
	v_mul_f32_e32 v16, 0x3fb8aa3b, v16
	v_exp_f32_e32 v16, v16
	s_nop 0
	v_cvt_f16_f32_e32 v16, v16
	global_store_short v[86:87], v16, off offset:32
	s_waitcnt vmcnt(1)
	v_add_f32_e32 v16, v20, v100
	v_mul_f32_e32 v16, 0xbfb8aa3b, v16
	v_exp_f32_e32 v16, v16
	s_nop 0
	v_add_f32_e32 v16, 1.0, v16
	v_rcp_f32_e32 v16, v16
	s_nop 0
	v_cvt_f16_f32_e32 v16, v16
	global_store_short v[86:87], v16, off offset:544
	v_add_f32_e32 v16, v17, v99
	v_mul_f32_e32 v16, 0xbfb8aa3b, v16
	v_exp_f32_e32 v16, v16
	s_nop 0
	v_add_f32_e32 v16, 1.0, v16
	v_rcp_f32_e32 v16, v16
	s_nop 0
	v_mul_f32_e32 v16, 0xbf1b4598, v16
	v_mul_f32_e32 v16, 0x3fb8aa3b, v16
	v_exp_f32_e32 v16, v16
	s_nop 0
	v_cvt_f16_f32_e32 v16, v16
	global_store_short v[88:89], v16, off offset:32
	v_add_f32_e32 v16, v21, v100
	v_mul_f32_e32 v16, 0xbfb8aa3b, v16
	v_exp_f32_e32 v16, v16
	s_nop 0
	v_add_f32_e32 v16, 1.0, v16
	v_rcp_f32_e32 v16, v16
	s_nop 0
	v_cvt_f16_f32_e32 v16, v16
	global_store_short v[88:89], v16, off offset:544
	v_add_f32_e32 v16, v18, v99
	v_mul_f32_e32 v16, 0xbfb8aa3b, v16
	v_exp_f32_e32 v16, v16
	s_nop 0
	v_add_f32_e32 v16, 1.0, v16
	v_rcp_f32_e32 v16, v16
	s_nop 0
	v_mul_f32_e32 v16, 0xbf1b4598, v16
	v_mul_f32_e32 v16, 0x3fb8aa3b, v16
	v_exp_f32_e32 v16, v16
	s_nop 0
	v_cvt_f16_f32_e32 v16, v16
	global_store_short v[90:91], v16, off offset:32
	v_add_f32_e32 v16, v22, v100
	v_mul_f32_e32 v16, 0xbfb8aa3b, v16
	v_exp_f32_e32 v16, v16
	s_nop 0
	v_add_f32_e32 v16, 1.0, v16
	v_rcp_f32_e32 v16, v16
	s_nop 0
	v_cvt_f16_f32_e32 v16, v16
	global_store_short v[90:91], v16, off offset:544
	v_add_f32_e32 v16, v19, v99
	v_mul_f32_e32 v16, 0xbfb8aa3b, v16
	v_exp_f32_e32 v16, v16
	s_nop 0
	v_add_f32_e32 v16, 1.0, v16
	v_rcp_f32_e32 v16, v16
	s_nop 0
	v_mul_f32_e32 v16, 0xbf1b4598, v16
	v_mul_f32_e32 v16, 0x3fb8aa3b, v16
	v_exp_f32_e32 v16, v16
	s_nop 0
	v_cvt_f16_f32_e32 v16, v16
	global_store_short v[84:85], v16, off offset:32
	v_add_f32_e32 v16, v23, v100
	v_mul_f32_e32 v16, 0xbfb8aa3b, v16
	v_exp_f32_e32 v16, v16
	s_nop 0
	v_add_f32_e32 v16, 1.0, v16
	v_rcp_f32_e32 v16, v16
	s_nop 0
	v_cvt_f16_f32_e32 v16, v16
	global_store_short v[84:85], v16, off offset:544
	global_load_dwordx4 v[20:23], v[52:53], off
	s_nop 0
	global_load_dwordx4 v[16:19], v[50:51], off
	s_waitcnt vmcnt(1)
	v_mfma_f32_16x16x32_f16 v[100:103], v[8:11], v[20:23], 0
	global_load_dwordx4 v[20:23], v[50:51], off offset:64
	s_waitcnt vmcnt(1)
	v_mfma_f32_16x16x32_f16 v[16:19], v[12:15], v[16:19], 0
	s_waitcnt vmcnt(0)
	v_mfma_f32_16x16x32_f16 v[20:23], v[4:7], v[20:23], v[16:19]
	s_nop 5
	global_load_dwordx4 v[16:19], v[54:55], off
	s_waitcnt vmcnt(0)
	v_mfma_f32_16x16x32_f16 v[16:19], v[0:3], v[16:19], v[100:103]
	s_nop 2
	global_load_dword v100, v[38:39], off offset:128
	global_load_dword v99, v[40:41], off offset:128
	s_waitcnt vmcnt(1)
	v_add_f32_e32 v20, v20, v100
	s_waitcnt vmcnt(0)
	v_add_f32_e32 v16, v16, v99
	v_mul_f32_e32 v16, 0xbfb8aa3b, v16
	v_exp_f32_e32 v16, v16
	v_mul_f32_e32 v20, 0xbfb8aa3b, v20
	v_exp_f32_e32 v20, v20
	v_add_f32_e32 v16, 1.0, v16
	v_rcp_f32_e32 v16, v16
	v_add_f32_e32 v20, 1.0, v20
	v_rcp_f32_e32 v20, v20
	v_cvt_f16_f32_e32 v16, v16
	v_mul_f32_e32 v20, 0xbf1b4598, v20
	v_mul_f32_e32 v20, 0x3fb8aa3b, v20
	global_store_short v[86:87], v16, off offset:576
	v_add_f32_e32 v16, v21, v100
	v_mul_f32_e32 v16, 0xbfb8aa3b, v16
	v_exp_f32_e32 v16, v16
	v_exp_f32_e32 v20, v20
	v_add_f32_e32 v16, 1.0, v16
	v_rcp_f32_e32 v16, v16
	v_cvt_f16_f32_e32 v20, v20
	v_mul_f32_e32 v16, 0xbf1b4598, v16
	v_mul_f32_e32 v16, 0x3fb8aa3b, v16
	v_exp_f32_e32 v16, v16
	global_store_short v[86:87], v20, off offset:64
	v_cvt_f16_f32_e32 v16, v16
	global_store_short v[88:89], v16, off offset:64
	v_add_f32_e32 v16, v17, v99
	v_mul_f32_e32 v16, 0xbfb8aa3b, v16
	v_exp_f32_e32 v16, v16
	s_nop 0
	v_add_f32_e32 v16, 1.0, v16
	v_rcp_f32_e32 v16, v16
	s_nop 0
	v_cvt_f16_f32_e32 v16, v16
	global_store_short v[88:89], v16, off offset:576
	v_add_f32_e32 v16, v22, v100
	v_mul_f32_e32 v16, 0xbfb8aa3b, v16
	v_exp_f32_e32 v16, v16
	s_nop 0
	v_add_f32_e32 v16, 1.0, v16
	v_rcp_f32_e32 v16, v16
	s_nop 0
	v_mul_f32_e32 v16, 0xbf1b4598, v16
	v_mul_f32_e32 v16, 0x3fb8aa3b, v16
	v_exp_f32_e32 v16, v16
	s_nop 0
	v_cvt_f16_f32_e32 v16, v16
	global_store_short v[90:91], v16, off offset:64
	v_add_f32_e32 v16, v18, v99
	v_mul_f32_e32 v16, 0xbfb8aa3b, v16
	v_exp_f32_e32 v16, v16
	s_nop 0
	v_add_f32_e32 v16, 1.0, v16
	v_rcp_f32_e32 v16, v16
	s_nop 0
	v_cvt_f16_f32_e32 v16, v16
	global_store_short v[90:91], v16, off offset:576
	v_add_f32_e32 v16, v23, v100
	v_mul_f32_e32 v16, 0xbfb8aa3b, v16
	v_exp_f32_e32 v16, v16
	s_nop 0
	v_add_f32_e32 v16, 1.0, v16
	v_rcp_f32_e32 v16, v16
	s_nop 0
	v_mul_f32_e32 v16, 0xbf1b4598, v16
	v_mul_f32_e32 v16, 0x3fb8aa3b, v16
	v_exp_f32_e32 v16, v16
	s_nop 0
	v_cvt_f16_f32_e32 v16, v16
	global_store_short v[84:85], v16, off offset:64
	v_add_f32_e32 v16, v19, v99
	v_mul_f32_e32 v16, 0xbfb8aa3b, v16
	v_exp_f32_e32 v16, v16
	s_nop 0
	v_add_f32_e32 v16, 1.0, v16
	v_rcp_f32_e32 v16, v16
	s_nop 0
	v_cvt_f16_f32_e32 v16, v16
	global_store_short v[84:85], v16, off offset:576
	global_load_dwordx4 v[16:19], v[56:57], off
	s_waitcnt vmcnt(0)
	v_mfma_f32_16x16x32_f16 v[12:15], v[12:15], v[16:19], 0
	global_load_dwordx4 v[16:19], v[58:59], off
	s_waitcnt vmcnt(0)
	v_mfma_f32_16x16x32_f16 v[8:11], v[8:11], v[16:19], 0
	global_load_dwordx4 v[16:19], v[56:57], off offset:64
	s_waitcnt vmcnt(0)
	v_mfma_f32_16x16x32_f16 v[4:7], v[4:7], v[16:19], v[12:15]
	s_nop 2
	global_load_dwordx4 v[12:15], v[60:61], off
	s_waitcnt vmcnt(0)
	v_mfma_f32_16x16x32_f16 v[0:3], v[0:3], v[12:15], v[8:11]
	s_nop 2
	global_load_dword v10, v[62:63], off
	global_load_dword v11, v[64:65], off
	v_lshl_add_u64 v[8:9], v[66:67], 0, v[76:77]
	s_waitcnt vmcnt(1)
	v_add_f32_e32 v4, v4, v10
	s_waitcnt vmcnt(0)
	v_add_f32_e32 v0, v0, v11
	v_mul_f32_e32 v0, 0xbfb8aa3b, v0
	v_exp_f32_e32 v0, v0
	v_mul_f32_e32 v4, 0xbfb8aa3b, v4
	v_exp_f32_e32 v4, v4
	v_add_f32_e32 v2, v2, v11
	v_add_f32_e32 v0, 1.0, v0
	v_rcp_f32_e32 v0, v0
	v_add_f32_e32 v4, 1.0, v4
	v_rcp_f32_e32 v4, v4
	v_mul_f32_e32 v2, 0xbfb8aa3b, v2
	v_cvt_f16_f32_e32 v0, v0
	v_exp_f32_e32 v2, v2
	v_mul_f32_e32 v4, 0xbf1b4598, v4
	v_mul_f32_e32 v4, 0x3fb8aa3b, v4
	global_store_short v[8:9], v0, off offset:512
	v_add_f32_e32 v0, v5, v10
	v_mul_f32_e32 v0, 0xbfb8aa3b, v0
	v_exp_f32_e32 v0, v0
	v_exp_f32_e32 v4, v4
	v_add_f32_e32 v2, 1.0, v2
	v_rcp_f32_e32 v2, v2
	v_add_f32_e32 v0, 1.0, v0
	v_rcp_f32_e32 v0, v0
	v_cvt_f16_f32_e32 v4, v4
	v_cvt_f16_f32_e32 v2, v2
	v_mul_f32_e32 v0, 0xbf1b4598, v0
	v_mul_f32_e32 v0, 0x3fb8aa3b, v0
	v_exp_f32_e32 v0, v0
	global_store_short v[8:9], v4, off
	v_lshl_add_u64 v[8:9], v[66:67], 0, v[78:79]
	v_add_f32_e32 v4, v6, v10
	v_cvt_f16_f32_e32 v0, v0
	v_mul_f32_e32 v4, 0xbfb8aa3b, v4
	v_exp_f32_e32 v4, v4
	global_store_short v[8:9], v0, off
	v_add_f32_e32 v0, v1, v11
	v_mul_f32_e32 v0, 0xbfb8aa3b, v0
	v_exp_f32_e32 v0, v0
	v_add_f32_e32 v4, 1.0, v4
	v_rcp_f32_e32 v4, v4
	v_add_f32_e32 v0, 1.0, v0
	v_rcp_f32_e32 v0, v0
	v_mul_f32_e32 v4, 0xbf1b4598, v4
	v_mul_f32_e32 v4, 0x3fb8aa3b, v4
	v_exp_f32_e32 v4, v4
	v_cvt_f16_f32_e32 v0, v0
	v_cvt_f16_f32_e32 v4, v4
	global_store_short v[8:9], v0, off offset:512
	v_lshl_add_u64 v[0:1], v[66:67], 0, v[80:81]
	global_store_short v[0:1], v2, off offset:512
	v_add_f32_e32 v2, v7, v10
	v_mul_f32_e32 v2, 0xbfb8aa3b, v2
	v_exp_f32_e32 v2, v2
	global_store_short v[0:1], v4, off
	v_lshl_add_u64 v[0:1], v[66:67], 0, v[82:83]
	v_add_f32_e32 v2, 1.0, v2
	v_rcp_f32_e32 v2, v2
	s_nop 0
	v_mul_f32_e32 v2, 0xbf1b4598, v2
	v_mul_f32_e32 v2, 0x3fb8aa3b, v2
	v_exp_f32_e32 v2, v2
	s_nop 0
	v_cvt_f16_f32_e32 v2, v2
	global_store_short v[0:1], v2, off
	v_add_f32_e32 v2, v3, v11
	v_mul_f32_e32 v2, 0xbfb8aa3b, v2
	v_exp_f32_e32 v2, v2
	s_nop 0
	v_add_f32_e32 v2, 1.0, v2
	v_rcp_f32_e32 v2, v2
	s_nop 0
	v_cvt_f16_f32_e32 v2, v2
	global_store_short v[0:1], v2, off offset:512
	v_add_u32_e32 v0, s3, v24
	v_ashrrev_i32_e32 v1, 31, v0
	v_lshlrev_b64 v[0:1], 11, v[0:1]
	v_lshl_add_u64 v[0:1], v[72:73], 0, v[0:1]
	global_load_dwordx4 v[184:187], v[0:1], off
	global_load_dwordx4 v[188:191], v[68:69], off
	global_load_dwordx4 v[192:195], v[0:1], off offset:64
	global_load_dwordx4 v[196:199], v[68:69], off offset:64
	global_load_dwordx4 v[200:203], v[0:1], off offset:128
	global_load_dwordx4 v[204:207], v[68:69], off offset:128
	global_load_dwordx4 v[208:211], v[0:1], off offset:192
	global_load_dwordx4 v[212:215], v[68:69], off offset:192
	global_load_dwordx4 v[216:219], v[0:1], off offset:256
	global_load_dwordx4 v[220:223], v[68:69], off offset:256
	global_load_dwordx4 v[224:227], v[0:1], off offset:320
	global_load_dwordx4 v[228:231], v[68:69], off offset:320
	global_load_dwordx4 v[232:235], v[0:1], off offset:384
	global_load_dwordx4 v[236:239], v[68:69], off offset:384
	global_load_dwordx4 v[240:243], v[0:1], off offset:448
	global_load_dwordx4 v[244:247], v[68:69], off offset:448
	s_add_i32 s3, s3, s8
	s_cmpk_lt_i32 s10, 0x440
	s_waitcnt vmcnt(14)
	v_mfma_f32_16x16x32_f16 v[2:5], v[184:187], v[188:191], 0
	s_waitcnt vmcnt(12)
	v_mfma_f32_16x16x32_f16 v[2:5], v[192:195], v[196:199], v[2:5]
	s_waitcnt vmcnt(10)
	v_mfma_f32_16x16x32_f16 v[2:5], v[200:203], v[204:207], v[2:5]
	s_waitcnt vmcnt(8)
	v_mfma_f32_16x16x32_f16 v[2:5], v[208:211], v[212:215], v[2:5]
	s_waitcnt vmcnt(6)
	v_mfma_f32_16x16x32_f16 v[2:5], v[216:219], v[220:223], v[2:5]
	s_waitcnt vmcnt(4)
	v_mfma_f32_16x16x32_f16 v[2:5], v[224:227], v[228:231], v[2:5]
	s_waitcnt vmcnt(2)
	v_mfma_f32_16x16x32_f16 v[2:5], v[232:235], v[236:239], v[2:5]
	s_waitcnt vmcnt(0)
	v_mfma_f32_16x16x32_f16 v[0:3], v[240:243], v[244:247], v[2:5]
	s_nop 3
	v_add_u32_e32 v4, 0x2000, v98
	s_nop 2
	ds_write2_b32 v4, v0, v1 offset1:16
	ds_write2_b32 v4, v2, v3 offset0:32 offset1:48
	s_waitcnt lgkmcnt(0)
	s_barrier
	ds_read_b32 v2, v96 offset:8192
	ds_read2st64_b32 v[0:1], v97 offset0:36 offset1:40
	s_waitcnt lgkmcnt(0)
	v_add_f32_e32 v0, v2, v0
	v_add_f32_e32 v0, v0, v1
	ds_read_b32 v1, v97 offset:11264
	s_waitcnt lgkmcnt(0)
	v_add_f32_e32 v0, v0, v1
	v_cvt_f16_f32_e32 v2, v0
	v_lshlrev_b32_e32 v0, 1, v24
	v_mov_b32_e32 v1, v27
	v_lshl_add_u64 v[0:1], v[74:75], 0, v[0:1]
	v_add_co_u32_e32 v0, vcc, 0x1000, v0
	s_nop 1
	v_addc_co_u32_e32 v1, vcc, 0, v1, vcc
	global_store_short v[0:1], v2, off offset:3584
	s_barrier
	s_cbranch_scc0 .LBB0_233
